# P2 transposer: both of a wave's items in flight before the first is processed (prologue de-serialisation), on v41
# baseline (speedup 1.0000x reference)
;     __device__ __forceinline__ float* ctl() const { return (float*)(ws + WS_CTL); }
;     __device__ __forceinline__ bf16_t* Win_t() const { return (bf16_t*)(ws + WS_WIN); }
;     __device__ __forceinline__ bf16_t* Wkv_t() const { return (bf16_t*)(ws + WS_WKV); }
;     __device__ __forceinline__ bf16_t* Wout_t() const { return (bf16_t*)(ws + WS_WOUT); }
;     __device__ __forceinline__ bf16_t* Wq_t() const { return (bf16_t*)(ws + WS_WQ); }
; template <int MODE>
; __device__ __forceinline__ void tr_item(const float* __restrict__ W, int N, bf16_t* WT, int ldk, int row_off, LAS float* scr, int kb, int nb, int lane,
;                                         const float* g, const float* b, float* c1, float* c2) {
;     const int k0 = 64 * kb, n0 = 32 * nb;
;     float tv[32];
; #pragma unroll
;     for (int i = 0; i < 32; ++i) tv[i] = __builtin_nontemporal_load(W + (size_t)(k0 + 2 * i + (lane >> 5)) * N + n0 + (lane & 31));
; __device__ __forceinline__ void p0_prologue(const Args& p, LAS unsigned char* lds, int G, int bid, int tid) {
;     ...
;     for (int it = gw; it < NITEMS; it += NGW) {
;         int r = it;
;         if (r < I_IN) { tr_item<1>(p.w_in(), DIN, p.Win_t(), DM, 0, scr, r / 48, r % 48, lane, nullptr, nullptr, nullptr, nullptr); continue; } r -= I_IN;
;         if (r < I_K) { tr_item<0>(p.xk_w(), DM, p.Wkv_t(), DM, 0, scr, r / 32, r % 32, lane, nullptr, nullptr, nullptr, nullptr); continue; } r -= I_K;
;         if (r < I_V) { tr_item<0>(p.xv_w(), DM, p.Wkv_t(), DM, DM, scr, r / 32, r % 32, lane, nullptr, nullptr, nullptr, nullptr); continue; } r -= I_V;
;         if (r < I_OUT) { tr_item<0>(p.w_out(), DM, p.Wout_t(), DM, 0, scr, r / 32, r % 32, lane, nullptr, nullptr, nullptr, nullptr); continue; } r -= I_OUT;
;         if (r < I_Q) { tr_item<2>(p.xq_w(), DM, p.Wq_t(), DM, 0, scr, r / 32, r % 32, lane, p.ln1_g(), p.ln1_b(), p.ctl() + CF_C1Q, p.ctl() + CF_C2Q); continue; } r -= I_Q;
;         if (r < I_O) { tr_item<0>(p.xo_w(), DM, p.Wo_t(), DM, 0, scr, r / 32, r % 32, lane, nullptr, nullptr, nullptr, nullptr); continue; } r -= I_O;
;         if (r < I_1) { tr_item<2>(p.w1(), DFF, p.W1_t(), DM, 0, scr, r / 128, r % 128, lane, p.ln2_g(), p.ln2_b(), p.ctl() + CF_C1H, p.ctl() + CF_C2H); continue; } r -= I_1;
;         tr_item<0>(p.w2(), DM, p.W2_t(), DFF, 0, scr, r / 32, r % 32, lane, nullptr, nullptr, nullptr, nullptr);
.Ltr2_vcu:
	s_cmp_lt_u32 s1, 64
	s_cbranch_scc1 .Ltr2_skip
	s_sub_u32 s1, s1, 64
	v_lshrrev_b32_e32 v32, 6, v192
	v_and_b32_e32 v33, 63, v192
	v_readfirstlane_b32 s0, v32
	s_load_dwordx2 s[8:9], s[100:101], 0xd0
	s_load_dwordx2 s[62:63], s[100:101], 0xa8
	s_load_dwordx2 s[64:65], s[100:101], 0x78
	s_nop 3
	s_lshl_b32 s1, s1, 3
	s_add_u32 s10, s1, s0
	s_sub_u32 s11, s96, 64
	s_lshl_b32 s11, s11, 3
	s_lshl_b32 s0, s0, 14
	v_lshrrev_b32_e32 v38, 5, v33
	v_and_b32_e32 v39, 31, v33
	v_lshlrev_b32_e32 v34, 12, v38
	v_lshl_add_u32 v34, v39, 2, v34
	v_mul_u32_u24_e32 v35, 0x84, v38
	v_lshl_add_u32 v35, v39, 2, v35
	v_add_u32_e32 v35, s0, v35
	v_and_b32_e32 v38, 7, v33
	v_lshrrev_b32_e32 v39, 3, v33
	v_mul_u32_u24_e32 v36, 0x420, v38
	v_lshl_add_u32 v36, v39, 2, v36
	v_add_u32_e32 v36, s0, v36
	v_lshlrev_b32_e32 v37, 13, v39
	v_lshl_add_u32 v37, v38, 4, v37
	v_lshlrev_b32_e32 v84, 11, v39
	v_lshl_add_u32 v84, v38, 4, v84
	s_waitcnt lgkmcnt(0)
	s_cmp_ge_u32 s10, 0x800
	s_cbranch_scc1 .Ltr2_loop
	s_lshr_b32 s0, s10, 5
	s_and_b32 s1, s10, 31
	s_mul_i32 s12, s0, 0x40000
	s_lshl_b32 s13, s1, 7
	s_add_u32 s12, s12, s13
	s_add_u32 s12, s8, s12
	s_addc_u32 s13, s9, 0
	global_load_dword v40, v34, s[12:13] nt
	s_add_u32 s12, s12, 0x2000
	s_addc_u32 s13, s13, 0
	global_load_dword v41, v34, s[12:13] nt
	s_add_u32 s12, s12, 0x2000
	s_addc_u32 s13, s13, 0
	global_load_dword v42, v34, s[12:13] nt
	s_add_u32 s12, s12, 0x2000
	s_addc_u32 s13, s13, 0
	global_load_dword v43, v34, s[12:13] nt
	s_add_u32 s12, s12, 0x2000
	s_addc_u32 s13, s13, 0
	global_load_dword v44, v34, s[12:13] nt
	s_add_u32 s12, s12, 0x2000
	s_addc_u32 s13, s13, 0
	global_load_dword v45, v34, s[12:13] nt
	s_add_u32 s12, s12, 0x2000
	s_addc_u32 s13, s13, 0
	global_load_dword v46, v34, s[12:13] nt
	s_add_u32 s12, s12, 0x2000
	s_addc_u32 s13, s13, 0
	global_load_dword v47, v34, s[12:13] nt
	s_add_u32 s12, s12, 0x2000
	s_addc_u32 s13, s13, 0
	global_load_dword v48, v34, s[12:13] nt
	s_add_u32 s12, s12, 0x2000
	s_addc_u32 s13, s13, 0
	global_load_dword v49, v34, s[12:13] nt
	s_add_u32 s12, s12, 0x2000
	s_addc_u32 s13, s13, 0
	global_load_dword v50, v34, s[12:13] nt
	s_add_u32 s12, s12, 0x2000
	s_addc_u32 s13, s13, 0
	global_load_dword v51, v34, s[12:13] nt
	s_add_u32 s12, s12, 0x2000
	s_addc_u32 s13, s13, 0
	global_load_dword v52, v34, s[12:13] nt
	s_add_u32 s12, s12, 0x2000
	s_addc_u32 s13, s13, 0
	global_load_dword v53, v34, s[12:13] nt
	s_add_u32 s12, s12, 0x2000
	s_addc_u32 s13, s13, 0
	global_load_dword v54, v34, s[12:13] nt
	s_add_u32 s12, s12, 0x2000
	s_addc_u32 s13, s13, 0
	global_load_dword v55, v34, s[12:13] nt
	s_add_u32 s12, s12, 0x2000
	s_addc_u32 s13, s13, 0
	global_load_dword v56, v34, s[12:13] nt
	s_add_u32 s12, s12, 0x2000
	s_addc_u32 s13, s13, 0
	global_load_dword v57, v34, s[12:13] nt
	s_add_u32 s12, s12, 0x2000
	s_addc_u32 s13, s13, 0
	global_load_dword v58, v34, s[12:13] nt
	s_add_u32 s12, s12, 0x2000
	s_addc_u32 s13, s13, 0
	global_load_dword v59, v34, s[12:13] nt
	s_add_u32 s12, s12, 0x2000
	s_addc_u32 s13, s13, 0
	global_load_dword v60, v34, s[12:13] nt
	s_add_u32 s12, s12, 0x2000
	s_addc_u32 s13, s13, 0
	global_load_dword v61, v34, s[12:13] nt
	s_add_u32 s12, s12, 0x2000
	s_addc_u32 s13, s13, 0
	global_load_dword v62, v34, s[12:13] nt
	s_add_u32 s12, s12, 0x2000
	s_addc_u32 s13, s13, 0
	global_load_dword v63, v34, s[12:13] nt
	s_add_u32 s12, s12, 0x2000
	s_addc_u32 s13, s13, 0
	global_load_dword v64, v34, s[12:13] nt
	s_add_u32 s12, s12, 0x2000
	s_addc_u32 s13, s13, 0
	global_load_dword v65, v34, s[12:13] nt
	s_add_u32 s12, s12, 0x2000
	s_addc_u32 s13, s13, 0
	global_load_dword v66, v34, s[12:13] nt
	s_add_u32 s12, s12, 0x2000
	s_addc_u32 s13, s13, 0
	global_load_dword v67, v34, s[12:13] nt
	s_add_u32 s12, s12, 0x2000
	s_addc_u32 s13, s13, 0
	global_load_dword v68, v34, s[12:13] nt
	s_add_u32 s12, s12, 0x2000
	s_addc_u32 s13, s13, 0
	global_load_dword v69, v34, s[12:13] nt
	s_add_u32 s12, s12, 0x2000
	s_addc_u32 s13, s13, 0
	global_load_dword v70, v34, s[12:13] nt
	s_add_u32 s12, s12, 0x2000
	s_addc_u32 s13, s13, 0
	global_load_dword v71, v34, s[12:13] nt
	s_add_u32 s67, s10, s11
	s_waitcnt vmcnt(32)
	s_cmp_ge_u32 s67, 0xb00
	s_cbranch_scc1 .Ltr2_only_a
	s_cmp_ge_u32 s67, 0xa00
	s_cbranch_scc1 .Ltr2_b_wout
	s_cmp_ge_u32 s67, 0x800
	s_cbranch_scc1 .Ltr2_b_wo
; #define LAS __attribute__((address_space(3)))
; __device__ __forceinline__ unsigned pk2(float lo, float hi) { f32x2v v = {lo, hi}; b16x2v b = __builtin_convertvector(v, b16x2v); return __builtin_bit_cast(unsigned, b); }
; template <int MODE>
; __device__ __forceinline__ void tr_item(const float* __restrict__ W, int N, bf16_t* WT, int ldk, int row_off, LAS float* scr, int kb, int nb, int lane,
;                                         const float* g, const float* b, float* c1, float* c2) {
;     ...
;     for (int i = 0; i < 32; ++i) tv[i] = __builtin_nontemporal_load(W + (size_t)(k0 + 2 * i + (lane >> 5)) * N + n0 + (lane & 31));
; #pragma unroll
;     for (int i = 0; i < 32; ++i) scr[(2 * i + (lane >> 5)) * 33 + (lane & 31)] = tv[i];
;     asm volatile("s_waitcnt lgkmcnt(0)" ::: "memory");
;     if (MODE == 2) {
;         const float* vec = (lane < 32) ? g : b; float s = 0.f;
; #pragma unroll 8
;         for (int k = 0; k < 64; ++k) s += vec[k0 + k] * scr[k * 33 + (lane & 31)];
;         atomicAdd(((lane < 32) ? c1 : c2) + n0 + (lane & 31), s);
;     }
;     const int c = lane & 7;
;     float gs[8];
; #pragma unroll
;     for (int i = 0; i < 8; ++i) gs[i] = (MODE == 2) ? g[k0 + 8 * c + i] : 1.0f;
; #pragma unroll
;     for (int j = 0; j < 4; ++j) { const int n = (lane >> 3) + 8 * j; const LAS float* s = scr + (8 * c) * 33 + n;
;         u32x4 o; o.x = pk2(s[0 * 33] * gs[0], s[1 * 33] * gs[1]); o.y = pk2(s[2 * 33] * gs[2], s[3 * 33] * gs[3]); o.z = pk2(s[4 * 33] * gs[4], s[5 * 33] * gs[5]); o.w = pk2(s[6 * 33] * gs[6], s[7 * 33] * gs[7]);
;         const int dr = (MODE == 1) ? win_dest(n0 + n) : (n0 + n);
;         *(u32x4*)(WT + (size_t)(row_off + dr) * ldk + k0 + 8 * c) = o; }
	s_lshr_b32 s0, s67, 5
	s_and_b32 s1, s67, 31
	s_mul_i32 s68, s0, 0x40000
	s_lshl_b32 s69, s1, 7
	s_add_u32 s68, s68, s69
	s_add_u32 s68, s8, s68
	s_addc_u32 s69, s9, 0
	global_load_dword v90, v34, s[68:69] nt
	s_add_u32 s68, s68, 0x2000
	s_addc_u32 s69, s69, 0
	global_load_dword v91, v34, s[68:69] nt
	s_add_u32 s68, s68, 0x2000
	s_addc_u32 s69, s69, 0
	global_load_dword v92, v34, s[68:69] nt
	s_add_u32 s68, s68, 0x2000
	s_addc_u32 s69, s69, 0
	global_load_dword v93, v34, s[68:69] nt
	s_add_u32 s68, s68, 0x2000
	s_addc_u32 s69, s69, 0
	global_load_dword v94, v34, s[68:69] nt
	s_add_u32 s68, s68, 0x2000
	s_addc_u32 s69, s69, 0
	global_load_dword v95, v34, s[68:69] nt
	s_add_u32 s68, s68, 0x2000
	s_addc_u32 s69, s69, 0
	global_load_dword v96, v34, s[68:69] nt
	s_add_u32 s68, s68, 0x2000
	s_addc_u32 s69, s69, 0
	global_load_dword v97, v34, s[68:69] nt
	s_add_u32 s68, s68, 0x2000
	s_addc_u32 s69, s69, 0
	global_load_dword v98, v34, s[68:69] nt
	s_add_u32 s68, s68, 0x2000
	s_addc_u32 s69, s69, 0
	global_load_dword v99, v34, s[68:69] nt
	s_add_u32 s68, s68, 0x2000
	s_addc_u32 s69, s69, 0
	global_load_dword v100, v34, s[68:69] nt
	s_add_u32 s68, s68, 0x2000
	s_addc_u32 s69, s69, 0
	global_load_dword v101, v34, s[68:69] nt
	s_add_u32 s68, s68, 0x2000
	s_addc_u32 s69, s69, 0
	global_load_dword v102, v34, s[68:69] nt
	s_add_u32 s68, s68, 0x2000
	s_addc_u32 s69, s69, 0
	global_load_dword v103, v34, s[68:69] nt
	s_add_u32 s68, s68, 0x2000
	s_addc_u32 s69, s69, 0
	global_load_dword v104, v34, s[68:69] nt
	s_add_u32 s68, s68, 0x2000
	s_addc_u32 s69, s69, 0
	global_load_dword v105, v34, s[68:69] nt
	s_add_u32 s68, s68, 0x2000
	s_addc_u32 s69, s69, 0
	global_load_dword v106, v34, s[68:69] nt
	s_add_u32 s68, s68, 0x2000
	s_addc_u32 s69, s69, 0
	global_load_dword v107, v34, s[68:69] nt
	s_add_u32 s68, s68, 0x2000
	s_addc_u32 s69, s69, 0
	global_load_dword v108, v34, s[68:69] nt
	s_add_u32 s68, s68, 0x2000
	s_addc_u32 s69, s69, 0
	global_load_dword v109, v34, s[68:69] nt
	s_add_u32 s68, s68, 0x2000
	s_addc_u32 s69, s69, 0
	global_load_dword v110, v34, s[68:69] nt
	s_add_u32 s68, s68, 0x2000
	s_addc_u32 s69, s69, 0
	global_load_dword v111, v34, s[68:69] nt
	s_add_u32 s68, s68, 0x2000
	s_addc_u32 s69, s69, 0
	global_load_dword v112, v34, s[68:69] nt
	s_add_u32 s68, s68, 0x2000
	s_addc_u32 s69, s69, 0
	global_load_dword v113, v34, s[68:69] nt
	s_add_u32 s68, s68, 0x2000
	s_addc_u32 s69, s69, 0
	global_load_dword v114, v34, s[68:69] nt
	s_add_u32 s68, s68, 0x2000
	s_addc_u32 s69, s69, 0
	global_load_dword v115, v34, s[68:69] nt
	s_add_u32 s68, s68, 0x2000
	s_addc_u32 s69, s69, 0
	global_load_dword v116, v34, s[68:69] nt
	s_add_u32 s68, s68, 0x2000
	s_addc_u32 s69, s69, 0
	global_load_dword v117, v34, s[68:69] nt
	s_add_u32 s68, s68, 0x2000
	s_addc_u32 s69, s69, 0
	global_load_dword v118, v34, s[68:69] nt
	s_add_u32 s68, s68, 0x2000
	s_addc_u32 s69, s69, 0
	global_load_dword v119, v34, s[68:69] nt
	s_add_u32 s68, s68, 0x2000
	s_addc_u32 s69, s69, 0
	global_load_dword v120, v34, s[68:69] nt
	s_add_u32 s68, s68, 0x2000
	s_addc_u32 s69, s69, 0
	s_lshr_b32 s0, s10, 5
	s_and_b32 s1, s10, 31
	s_mul_i32 s12, s1, 0x40000
	s_lshl_b32 s13, s0, 7
	s_add_u32 s12, s12, s13
	s_add_u32 s12, s12, 0x1700000
	s_add_u32 s12, s58, s12
	s_addc_u32 s13, s59, 0
	s_waitcnt vmcnt(62)
	global_load_dword v121, v34, s[68:69] nt
	ds_write_b32 v35, v40
	s_waitcnt vmcnt(62)
	ds_write_b32 v35, v41 offset:264
	s_waitcnt vmcnt(61)
	ds_write_b32 v35, v42 offset:528
	s_waitcnt vmcnt(60)
	ds_write_b32 v35, v43 offset:792
	s_waitcnt vmcnt(59)
	ds_write_b32 v35, v44 offset:1056
	s_waitcnt vmcnt(58)
	ds_write_b32 v35, v45 offset:1320
	s_waitcnt vmcnt(57)
	ds_write_b32 v35, v46 offset:1584
	s_waitcnt vmcnt(56)
	ds_write_b32 v35, v47 offset:1848
	s_waitcnt vmcnt(55)
	ds_write_b32 v35, v48 offset:2112
	s_waitcnt vmcnt(54)
	ds_write_b32 v35, v49 offset:2376
	s_waitcnt vmcnt(53)
	ds_write_b32 v35, v50 offset:2640
	s_waitcnt vmcnt(52)
	ds_write_b32 v35, v51 offset:2904
	s_waitcnt vmcnt(51)
	ds_write_b32 v35, v52 offset:3168
	s_waitcnt vmcnt(50)
	ds_write_b32 v35, v53 offset:3432
	s_waitcnt vmcnt(49)
	ds_write_b32 v35, v54 offset:3696
	s_waitcnt vmcnt(48)
	ds_write_b32 v35, v55 offset:3960
	s_waitcnt vmcnt(47)
	ds_write_b32 v35, v56 offset:4224
	s_waitcnt vmcnt(46)
	ds_write_b32 v35, v57 offset:4488
	s_waitcnt vmcnt(45)
	ds_write_b32 v35, v58 offset:4752
	s_waitcnt vmcnt(44)
	ds_write_b32 v35, v59 offset:5016
	s_waitcnt vmcnt(43)
	ds_write_b32 v35, v60 offset:5280
	s_waitcnt vmcnt(42)
	ds_write_b32 v35, v61 offset:5544
	s_waitcnt vmcnt(41)
	ds_write_b32 v35, v62 offset:5808
	s_waitcnt vmcnt(40)
	ds_write_b32 v35, v63 offset:6072
	s_waitcnt vmcnt(39)
	ds_write_b32 v35, v64 offset:6336
	s_waitcnt vmcnt(38)
	ds_write_b32 v35, v65 offset:6600
	s_waitcnt vmcnt(37)
	ds_write_b32 v35, v66 offset:6864
	s_waitcnt vmcnt(36)
	ds_write_b32 v35, v67 offset:7128
	s_waitcnt vmcnt(35)
	ds_write_b32 v35, v68 offset:7392
	s_waitcnt vmcnt(34)
	ds_write_b32 v35, v69 offset:7656
	s_waitcnt vmcnt(33)
	ds_write_b32 v35, v70 offset:7920
	s_waitcnt vmcnt(32)
	ds_write_b32 v35, v71 offset:8184
	s_waitcnt lgkmcnt(0)
	ds_read2_b32 v[72:73], v36 offset1:33
	ds_read2_b32 v[74:75], v36 offset0:66 offset1:99
	ds_read2_b32 v[76:77], v36 offset0:132 offset1:165
	ds_read2_b32 v[78:79], v36 offset0:198 offset1:231
	s_waitcnt lgkmcnt(0)
	v_cvt_pk_bf16_f32 v80, v72, v73
	v_cvt_pk_bf16_f32 v81, v74, v75
	v_cvt_pk_bf16_f32 v82, v76, v77
	v_cvt_pk_bf16_f32 v83, v78, v79
	global_store_dwordx4 v37, v[80:83], s[12:13]
	s_add_u32 s12, s12, 0x10000
	s_addc_u32 s13, s13, 0
	ds_read2_b32 v[72:73], v36 offset0:8 offset1:41
	ds_read2_b32 v[74:75], v36 offset0:74 offset1:107
	ds_read2_b32 v[76:77], v36 offset0:140 offset1:173
	ds_read2_b32 v[78:79], v36 offset0:206 offset1:239
	s_waitcnt lgkmcnt(0)
; #define LAS __attribute__((address_space(3)))
; __device__ __forceinline__ unsigned pk2(float lo, float hi) { f32x2v v = {lo, hi}; b16x2v b = __builtin_convertvector(v, b16x2v); return __builtin_bit_cast(unsigned, b); }
; template <int MODE>
; __device__ __forceinline__ void tr_item(const float* __restrict__ W, int N, bf16_t* WT, int ldk, int row_off, LAS float* scr, int kb, int nb, int lane,
;                                         const float* g, const float* b, float* c1, float* c2) {
;     ...
;     const int c = lane & 7;
;     float gs[8];
; #pragma unroll
;     for (int i = 0; i < 8; ++i) gs[i] = (MODE == 2) ? g[k0 + 8 * c + i] : 1.0f;
; #pragma unroll
;     for (int j = 0; j < 4; ++j) { const int n = (lane >> 3) + 8 * j; const LAS float* s = scr + (8 * c) * 33 + n;
;         u32x4 o; o.x = pk2(s[0 * 33] * gs[0], s[1 * 33] * gs[1]); o.y = pk2(s[2 * 33] * gs[2], s[3 * 33] * gs[3]); o.z = pk2(s[4 * 33] * gs[4], s[5 * 33] * gs[5]); o.w = pk2(s[6 * 33] * gs[6], s[7 * 33] * gs[7]);
;         const int dr = (MODE == 1) ? win_dest(n0 + n) : (n0 + n);
;         *(u32x4*)(WT + (size_t)(row_off + dr) * ldk + k0 + 8 * c) = o; }
;     asm volatile("s_waitcnt lgkmcnt(0)" ::: "memory");
	v_cvt_pk_bf16_f32 v80, v72, v73
	v_cvt_pk_bf16_f32 v81, v74, v75
	v_cvt_pk_bf16_f32 v82, v76, v77
	v_cvt_pk_bf16_f32 v83, v78, v79
	global_store_dwordx4 v37, v[80:83], s[12:13]
	s_add_u32 s12, s12, 0x10000
	s_addc_u32 s13, s13, 0
	ds_read2_b32 v[72:73], v36 offset0:16 offset1:49
	ds_read2_b32 v[74:75], v36 offset0:82 offset1:115
	ds_read2_b32 v[76:77], v36 offset0:148 offset1:181
	ds_read2_b32 v[78:79], v36 offset0:214 offset1:247
	s_waitcnt lgkmcnt(0)
	v_cvt_pk_bf16_f32 v80, v72, v73
	v_cvt_pk_bf16_f32 v81, v74, v75
	v_cvt_pk_bf16_f32 v82, v76, v77
	v_cvt_pk_bf16_f32 v83, v78, v79
	global_store_dwordx4 v37, v[80:83], s[12:13]
	s_add_u32 s12, s12, 0x10000
	s_addc_u32 s13, s13, 0
	ds_read2_b32 v[72:73], v36 offset0:24 offset1:57
	ds_read2_b32 v[74:75], v36 offset0:90 offset1:123
	ds_read2_b32 v[76:77], v36 offset0:156 offset1:189
	ds_read2_b32 v[78:79], v36 offset0:222 offset1:255
	s_waitcnt lgkmcnt(0)
	v_cvt_pk_bf16_f32 v80, v72, v73
	v_cvt_pk_bf16_f32 v81, v74, v75
	v_cvt_pk_bf16_f32 v82, v76, v77
	v_cvt_pk_bf16_f32 v83, v78, v79
	global_store_dwordx4 v37, v[80:83], s[12:13]
	s_lshr_b32 s0, s67, 5
	s_and_b32 s1, s67, 31
	s_mul_i32 s12, s1, 0x40000
	s_lshl_b32 s13, s0, 7
	s_add_u32 s12, s12, s13
	s_add_u32 s12, s12, 0x1700000
	s_add_u32 s12, s58, s12
	s_addc_u32 s13, s59, 0
	s_waitcnt vmcnt(35)
	ds_write_b32 v35, v90
	s_waitcnt vmcnt(34)
	ds_write_b32 v35, v91 offset:264
	s_waitcnt vmcnt(33)
	ds_write_b32 v35, v92 offset:528
	s_waitcnt vmcnt(32)
	ds_write_b32 v35, v93 offset:792
	s_waitcnt vmcnt(31)
	ds_write_b32 v35, v94 offset:1056
	s_waitcnt vmcnt(30)
	ds_write_b32 v35, v95 offset:1320
	s_waitcnt vmcnt(29)
	ds_write_b32 v35, v96 offset:1584
	s_waitcnt vmcnt(28)
	ds_write_b32 v35, v97 offset:1848
	s_waitcnt vmcnt(27)
	ds_write_b32 v35, v98 offset:2112
	s_waitcnt vmcnt(26)
	ds_write_b32 v35, v99 offset:2376
	s_waitcnt vmcnt(25)
	ds_write_b32 v35, v100 offset:2640
	s_waitcnt vmcnt(24)
	ds_write_b32 v35, v101 offset:2904
	s_waitcnt vmcnt(23)
	ds_write_b32 v35, v102 offset:3168
	s_waitcnt vmcnt(22)
	ds_write_b32 v35, v103 offset:3432
	s_waitcnt vmcnt(21)
	ds_write_b32 v35, v104 offset:3696
	s_waitcnt vmcnt(20)
	ds_write_b32 v35, v105 offset:3960
	s_waitcnt vmcnt(19)
	ds_write_b32 v35, v106 offset:4224
	s_waitcnt vmcnt(18)
	ds_write_b32 v35, v107 offset:4488
	s_waitcnt vmcnt(17)
	ds_write_b32 v35, v108 offset:4752
	s_waitcnt vmcnt(16)
	ds_write_b32 v35, v109 offset:5016
	s_waitcnt vmcnt(15)
	ds_write_b32 v35, v110 offset:5280
	s_waitcnt vmcnt(14)
	ds_write_b32 v35, v111 offset:5544
	s_waitcnt vmcnt(13)
	ds_write_b32 v35, v112 offset:5808
	s_waitcnt vmcnt(12)
	ds_write_b32 v35, v113 offset:6072
	s_waitcnt vmcnt(11)
	ds_write_b32 v35, v114 offset:6336
	s_waitcnt vmcnt(10)
	ds_write_b32 v35, v115 offset:6600
	s_waitcnt vmcnt(9)
	ds_write_b32 v35, v116 offset:6864
	s_waitcnt vmcnt(8)
	ds_write_b32 v35, v117 offset:7128
	s_waitcnt vmcnt(7)
	ds_write_b32 v35, v118 offset:7392
	s_waitcnt vmcnt(6)
	ds_write_b32 v35, v119 offset:7656
	s_waitcnt vmcnt(5)
	ds_write_b32 v35, v120 offset:7920
	s_waitcnt vmcnt(4)
	ds_write_b32 v35, v121 offset:8184
	s_waitcnt lgkmcnt(0)
	ds_read2_b32 v[72:73], v36 offset1:33
	ds_read2_b32 v[74:75], v36 offset0:66 offset1:99
	ds_read2_b32 v[76:77], v36 offset0:132 offset1:165
	ds_read2_b32 v[78:79], v36 offset0:198 offset1:231
	s_waitcnt lgkmcnt(0)
	v_cvt_pk_bf16_f32 v80, v72, v73
	v_cvt_pk_bf16_f32 v81, v74, v75
	v_cvt_pk_bf16_f32 v82, v76, v77
	v_cvt_pk_bf16_f32 v83, v78, v79
	global_store_dwordx4 v37, v[80:83], s[12:13]
	s_add_u32 s12, s12, 0x10000
	s_addc_u32 s13, s13, 0
	ds_read2_b32 v[72:73], v36 offset0:8 offset1:41
	ds_read2_b32 v[74:75], v36 offset0:74 offset1:107
	ds_read2_b32 v[76:77], v36 offset0:140 offset1:173
	ds_read2_b32 v[78:79], v36 offset0:206 offset1:239
	s_waitcnt lgkmcnt(0)
	v_cvt_pk_bf16_f32 v80, v72, v73
	v_cvt_pk_bf16_f32 v81, v74, v75
	v_cvt_pk_bf16_f32 v82, v76, v77
	v_cvt_pk_bf16_f32 v83, v78, v79
	global_store_dwordx4 v37, v[80:83], s[12:13]
	s_add_u32 s12, s12, 0x10000
	s_addc_u32 s13, s13, 0
	ds_read2_b32 v[72:73], v36 offset0:16 offset1:49
	ds_read2_b32 v[74:75], v36 offset0:82 offset1:115
	ds_read2_b32 v[76:77], v36 offset0:148 offset1:181
	ds_read2_b32 v[78:79], v36 offset0:214 offset1:247
	s_waitcnt lgkmcnt(0)
	v_cvt_pk_bf16_f32 v80, v72, v73
	v_cvt_pk_bf16_f32 v81, v74, v75
	v_cvt_pk_bf16_f32 v82, v76, v77
	v_cvt_pk_bf16_f32 v83, v78, v79
	global_store_dwordx4 v37, v[80:83], s[12:13]
	s_add_u32 s12, s12, 0x10000
	s_addc_u32 s13, s13, 0
	ds_read2_b32 v[72:73], v36 offset0:24 offset1:57
	ds_read2_b32 v[74:75], v36 offset0:90 offset1:123
	ds_read2_b32 v[76:77], v36 offset0:156 offset1:189
	ds_read2_b32 v[78:79], v36 offset0:222 offset1:255
	s_waitcnt lgkmcnt(0)
	v_cvt_pk_bf16_f32 v80, v72, v73
	v_cvt_pk_bf16_f32 v81, v74, v75
	v_cvt_pk_bf16_f32 v82, v76, v77
	v_cvt_pk_bf16_f32 v83, v78, v79
	global_store_dwordx4 v37, v[80:83], s[12:13]
	s_branch .Ltr2_pair_done
; #define LAS __attribute__((address_space(3)))
; __device__ __forceinline__ unsigned pk2(float lo, float hi) { f32x2v v = {lo, hi}; b16x2v b = __builtin_convertvector(v, b16x2v); return __builtin_bit_cast(unsigned, b); }
;     __device__ __forceinline__ bf16_t* Wo_t() const { return (bf16_t*)(ws + WS_WO); }
; template <int MODE>
; __device__ __forceinline__ void tr_item(const float* __restrict__ W, int N, bf16_t* WT, int ldk, int row_off, LAS float* scr, int kb, int nb, int lane,
;                                         const float* g, const float* b, float* c1, float* c2) {
;     ...
;     for (int i = 0; i < 32; ++i) tv[i] = __builtin_nontemporal_load(W + (size_t)(k0 + 2 * i + (lane >> 5)) * N + n0 + (lane & 31));
; #pragma unroll
;     for (int i = 0; i < 32; ++i) scr[(2 * i + (lane >> 5)) * 33 + (lane & 31)] = tv[i];
;     asm volatile("s_waitcnt lgkmcnt(0)" ::: "memory");
;     if (MODE == 2) {
;         const float* vec = (lane < 32) ? g : b; float s = 0.f;
; #pragma unroll 8
;         for (int k = 0; k < 64; ++k) s += vec[k0 + k] * scr[k * 33 + (lane & 31)];
;         atomicAdd(((lane < 32) ? c1 : c2) + n0 + (lane & 31), s);
;     }
;     const int c = lane & 7;
;     float gs[8];
; #pragma unroll
;     for (int i = 0; i < 8; ++i) gs[i] = (MODE == 2) ? g[k0 + 8 * c + i] : 1.0f;
; #pragma unroll
;     for (int j = 0; j < 4; ++j) { const int n = (lane >> 3) + 8 * j; const LAS float* s = scr + (8 * c) * 33 + n;
;         u32x4 o; o.x = pk2(s[0 * 33] * gs[0], s[1 * 33] * gs[1]); o.y = pk2(s[2 * 33] * gs[2], s[3 * 33] * gs[3]); o.z = pk2(s[4 * 33] * gs[4], s[5 * 33] * gs[5]); o.w = pk2(s[6 * 33] * gs[6], s[7 * 33] * gs[7]);
;         const int dr = (MODE == 1) ? win_dest(n0 + n) : (n0 + n);
;         *(u32x4*)(WT + (size_t)(row_off + dr) * ldk + k0 + 8 * c) = o; }
; __device__ __forceinline__ void p0_prologue(const Args& p, LAS unsigned char* lds, int G, int bid, int tid) {
;     ...
;         if (r < I_O) { tr_item<0>(p.xo_w(), DM, p.Wo_t(), DM, 0, scr, r / 32, r % 32, lane, nullptr, nullptr, nullptr, nullptr); continue; } r -= I_O;
.Ltr2_b_wo:
	s_sub_u32 s66, s67, 0x800
	s_lshr_b32 s0, s66, 5
	s_and_b32 s1, s66, 31
	s_mul_i32 s68, s0, 0x40000
	s_lshl_b32 s69, s1, 7
	s_add_u32 s68, s68, s69
	s_add_u32 s68, s62, s68
	s_addc_u32 s69, s63, 0
	global_load_dword v90, v34, s[68:69] nt
	s_add_u32 s68, s68, 0x2000
	s_addc_u32 s69, s69, 0
	global_load_dword v91, v34, s[68:69] nt
	s_add_u32 s68, s68, 0x2000
	s_addc_u32 s69, s69, 0
	global_load_dword v92, v34, s[68:69] nt
	s_add_u32 s68, s68, 0x2000
	s_addc_u32 s69, s69, 0
	global_load_dword v93, v34, s[68:69] nt
	s_add_u32 s68, s68, 0x2000
	s_addc_u32 s69, s69, 0
	global_load_dword v94, v34, s[68:69] nt
	s_add_u32 s68, s68, 0x2000
	s_addc_u32 s69, s69, 0
	global_load_dword v95, v34, s[68:69] nt
	s_add_u32 s68, s68, 0x2000
	s_addc_u32 s69, s69, 0
	global_load_dword v96, v34, s[68:69] nt
	s_add_u32 s68, s68, 0x2000
	s_addc_u32 s69, s69, 0
	global_load_dword v97, v34, s[68:69] nt
	s_add_u32 s68, s68, 0x2000
	s_addc_u32 s69, s69, 0
	global_load_dword v98, v34, s[68:69] nt
	s_add_u32 s68, s68, 0x2000
	s_addc_u32 s69, s69, 0
	global_load_dword v99, v34, s[68:69] nt
	s_add_u32 s68, s68, 0x2000
	s_addc_u32 s69, s69, 0
	global_load_dword v100, v34, s[68:69] nt
	s_add_u32 s68, s68, 0x2000
	s_addc_u32 s69, s69, 0
	global_load_dword v101, v34, s[68:69] nt
	s_add_u32 s68, s68, 0x2000
	s_addc_u32 s69, s69, 0
	global_load_dword v102, v34, s[68:69] nt
	s_add_u32 s68, s68, 0x2000
	s_addc_u32 s69, s69, 0
	global_load_dword v103, v34, s[68:69] nt
	s_add_u32 s68, s68, 0x2000
	s_addc_u32 s69, s69, 0
	global_load_dword v104, v34, s[68:69] nt
	s_add_u32 s68, s68, 0x2000
	s_addc_u32 s69, s69, 0
	global_load_dword v105, v34, s[68:69] nt
	s_add_u32 s68, s68, 0x2000
	s_addc_u32 s69, s69, 0
	global_load_dword v106, v34, s[68:69] nt
	s_add_u32 s68, s68, 0x2000
	s_addc_u32 s69, s69, 0
	global_load_dword v107, v34, s[68:69] nt
	s_add_u32 s68, s68, 0x2000
	s_addc_u32 s69, s69, 0
	global_load_dword v108, v34, s[68:69] nt
	s_add_u32 s68, s68, 0x2000
	s_addc_u32 s69, s69, 0
	global_load_dword v109, v34, s[68:69] nt
	s_add_u32 s68, s68, 0x2000
	s_addc_u32 s69, s69, 0
	global_load_dword v110, v34, s[68:69] nt
	s_add_u32 s68, s68, 0x2000
	s_addc_u32 s69, s69, 0
	global_load_dword v111, v34, s[68:69] nt
	s_add_u32 s68, s68, 0x2000
	s_addc_u32 s69, s69, 0
	global_load_dword v112, v34, s[68:69] nt
	s_add_u32 s68, s68, 0x2000
	s_addc_u32 s69, s69, 0
	global_load_dword v113, v34, s[68:69] nt
	s_add_u32 s68, s68, 0x2000
	s_addc_u32 s69, s69, 0
	global_load_dword v114, v34, s[68:69] nt
	s_add_u32 s68, s68, 0x2000
	s_addc_u32 s69, s69, 0
	global_load_dword v115, v34, s[68:69] nt
	s_add_u32 s68, s68, 0x2000
	s_addc_u32 s69, s69, 0
	global_load_dword v116, v34, s[68:69] nt
	s_add_u32 s68, s68, 0x2000
	s_addc_u32 s69, s69, 0
	global_load_dword v117, v34, s[68:69] nt
	s_add_u32 s68, s68, 0x2000
	s_addc_u32 s69, s69, 0
	global_load_dword v118, v34, s[68:69] nt
	s_add_u32 s68, s68, 0x2000
	s_addc_u32 s69, s69, 0
	global_load_dword v119, v34, s[68:69] nt
	s_add_u32 s68, s68, 0x2000
	s_addc_u32 s69, s69, 0
	global_load_dword v120, v34, s[68:69] nt
	s_add_u32 s68, s68, 0x2000
	s_addc_u32 s69, s69, 0
	s_lshr_b32 s0, s10, 5
	s_and_b32 s1, s10, 31
	s_mul_i32 s12, s1, 0x40000
	s_lshl_b32 s13, s0, 7
	s_add_u32 s12, s12, s13
	s_add_u32 s12, s12, 0x1700000
	s_add_u32 s12, s58, s12
	s_addc_u32 s13, s59, 0
	s_waitcnt vmcnt(62)
	global_load_dword v121, v34, s[68:69] nt
	ds_write_b32 v35, v40
	s_waitcnt vmcnt(62)
	ds_write_b32 v35, v41 offset:264
	s_waitcnt vmcnt(61)
	ds_write_b32 v35, v42 offset:528
	s_waitcnt vmcnt(60)
	ds_write_b32 v35, v43 offset:792
	s_waitcnt vmcnt(59)
	ds_write_b32 v35, v44 offset:1056
	s_waitcnt vmcnt(58)
	ds_write_b32 v35, v45 offset:1320
	s_waitcnt vmcnt(57)
	ds_write_b32 v35, v46 offset:1584
	s_waitcnt vmcnt(56)
	ds_write_b32 v35, v47 offset:1848
	s_waitcnt vmcnt(55)
	ds_write_b32 v35, v48 offset:2112
	s_waitcnt vmcnt(54)
	ds_write_b32 v35, v49 offset:2376
	s_waitcnt vmcnt(53)
	ds_write_b32 v35, v50 offset:2640
	s_waitcnt vmcnt(52)
	ds_write_b32 v35, v51 offset:2904
	s_waitcnt vmcnt(51)
	ds_write_b32 v35, v52 offset:3168
	s_waitcnt vmcnt(50)
	ds_write_b32 v35, v53 offset:3432
	s_waitcnt vmcnt(49)
	ds_write_b32 v35, v54 offset:3696
	s_waitcnt vmcnt(48)
	ds_write_b32 v35, v55 offset:3960
	s_waitcnt vmcnt(47)
	ds_write_b32 v35, v56 offset:4224
	s_waitcnt vmcnt(46)
	ds_write_b32 v35, v57 offset:4488
	s_waitcnt vmcnt(45)
	ds_write_b32 v35, v58 offset:4752
	s_waitcnt vmcnt(44)
	ds_write_b32 v35, v59 offset:5016
	s_waitcnt vmcnt(43)
	ds_write_b32 v35, v60 offset:5280
	s_waitcnt vmcnt(42)
	ds_write_b32 v35, v61 offset:5544
	s_waitcnt vmcnt(41)
	ds_write_b32 v35, v62 offset:5808
	s_waitcnt vmcnt(40)
	ds_write_b32 v35, v63 offset:6072
	s_waitcnt vmcnt(39)
	ds_write_b32 v35, v64 offset:6336
	s_waitcnt vmcnt(38)
	ds_write_b32 v35, v65 offset:6600
	s_waitcnt vmcnt(37)
	ds_write_b32 v35, v66 offset:6864
	s_waitcnt vmcnt(36)
	ds_write_b32 v35, v67 offset:7128
	s_waitcnt vmcnt(35)
	ds_write_b32 v35, v68 offset:7392
	s_waitcnt vmcnt(34)
	ds_write_b32 v35, v69 offset:7656
	s_waitcnt vmcnt(33)
	ds_write_b32 v35, v70 offset:7920
	s_waitcnt vmcnt(32)
	ds_write_b32 v35, v71 offset:8184
	s_waitcnt lgkmcnt(0)
	ds_read2_b32 v[72:73], v36 offset1:33
	ds_read2_b32 v[74:75], v36 offset0:66 offset1:99
	ds_read2_b32 v[76:77], v36 offset0:132 offset1:165
	ds_read2_b32 v[78:79], v36 offset0:198 offset1:231
	s_waitcnt lgkmcnt(0)
	v_cvt_pk_bf16_f32 v80, v72, v73
	v_cvt_pk_bf16_f32 v81, v74, v75
	v_cvt_pk_bf16_f32 v82, v76, v77
	v_cvt_pk_bf16_f32 v83, v78, v79
	global_store_dwordx4 v37, v[80:83], s[12:13]
	s_add_u32 s12, s12, 0x10000
	s_addc_u32 s13, s13, 0
	ds_read2_b32 v[72:73], v36 offset0:8 offset1:41
	ds_read2_b32 v[74:75], v36 offset0:74 offset1:107
	ds_read2_b32 v[76:77], v36 offset0:140 offset1:173
	ds_read2_b32 v[78:79], v36 offset0:206 offset1:239
	s_waitcnt lgkmcnt(0)
; #define LAS __attribute__((address_space(3)))
; __device__ __forceinline__ unsigned pk2(float lo, float hi) { f32x2v v = {lo, hi}; b16x2v b = __builtin_convertvector(v, b16x2v); return __builtin_bit_cast(unsigned, b); }
; template <int MODE>
; __device__ __forceinline__ void tr_item(const float* __restrict__ W, int N, bf16_t* WT, int ldk, int row_off, LAS float* scr, int kb, int nb, int lane,
;                                         const float* g, const float* b, float* c1, float* c2) {
;     ...
;     const int c = lane & 7;
;     float gs[8];
; #pragma unroll
;     for (int i = 0; i < 8; ++i) gs[i] = (MODE == 2) ? g[k0 + 8 * c + i] : 1.0f;
; #pragma unroll
;     for (int j = 0; j < 4; ++j) { const int n = (lane >> 3) + 8 * j; const LAS float* s = scr + (8 * c) * 33 + n;
;         u32x4 o; o.x = pk2(s[0 * 33] * gs[0], s[1 * 33] * gs[1]); o.y = pk2(s[2 * 33] * gs[2], s[3 * 33] * gs[3]); o.z = pk2(s[4 * 33] * gs[4], s[5 * 33] * gs[5]); o.w = pk2(s[6 * 33] * gs[6], s[7 * 33] * gs[7]);
;         const int dr = (MODE == 1) ? win_dest(n0 + n) : (n0 + n);
;         *(u32x4*)(WT + (size_t)(row_off + dr) * ldk + k0 + 8 * c) = o; }
;     asm volatile("s_waitcnt lgkmcnt(0)" ::: "memory");
	v_cvt_pk_bf16_f32 v80, v72, v73
	v_cvt_pk_bf16_f32 v81, v74, v75
	v_cvt_pk_bf16_f32 v82, v76, v77
	v_cvt_pk_bf16_f32 v83, v78, v79
	global_store_dwordx4 v37, v[80:83], s[12:13]
	s_add_u32 s12, s12, 0x10000
	s_addc_u32 s13, s13, 0
	ds_read2_b32 v[72:73], v36 offset0:16 offset1:49
	ds_read2_b32 v[74:75], v36 offset0:82 offset1:115
	ds_read2_b32 v[76:77], v36 offset0:148 offset1:181
	ds_read2_b32 v[78:79], v36 offset0:214 offset1:247
	s_waitcnt lgkmcnt(0)
	v_cvt_pk_bf16_f32 v80, v72, v73
	v_cvt_pk_bf16_f32 v81, v74, v75
	v_cvt_pk_bf16_f32 v82, v76, v77
	v_cvt_pk_bf16_f32 v83, v78, v79
	global_store_dwordx4 v37, v[80:83], s[12:13]
	s_add_u32 s12, s12, 0x10000
	s_addc_u32 s13, s13, 0
	ds_read2_b32 v[72:73], v36 offset0:24 offset1:57
	ds_read2_b32 v[74:75], v36 offset0:90 offset1:123
	ds_read2_b32 v[76:77], v36 offset0:156 offset1:189
	ds_read2_b32 v[78:79], v36 offset0:222 offset1:255
	s_waitcnt lgkmcnt(0)
	v_cvt_pk_bf16_f32 v80, v72, v73
	v_cvt_pk_bf16_f32 v81, v74, v75
	v_cvt_pk_bf16_f32 v82, v76, v77
	v_cvt_pk_bf16_f32 v83, v78, v79
	global_store_dwordx4 v37, v[80:83], s[12:13]
	s_lshr_b32 s0, s66, 5
	s_and_b32 s1, s66, 31
	s_mul_i32 s12, s1, 0x10000
	s_lshl_b32 s13, s0, 7
	s_add_u32 s12, s12, s13
	s_add_u32 s12, s12, 0xd00000
	s_add_u32 s12, s58, s12
	s_addc_u32 s13, s59, 0
	s_waitcnt vmcnt(35)
	ds_write_b32 v35, v90
	s_waitcnt vmcnt(34)
	ds_write_b32 v35, v91 offset:264
	s_waitcnt vmcnt(33)
	ds_write_b32 v35, v92 offset:528
	s_waitcnt vmcnt(32)
	ds_write_b32 v35, v93 offset:792
	s_waitcnt vmcnt(31)
	ds_write_b32 v35, v94 offset:1056
	s_waitcnt vmcnt(30)
	ds_write_b32 v35, v95 offset:1320
	s_waitcnt vmcnt(29)
	ds_write_b32 v35, v96 offset:1584
	s_waitcnt vmcnt(28)
	ds_write_b32 v35, v97 offset:1848
	s_waitcnt vmcnt(27)
	ds_write_b32 v35, v98 offset:2112
	s_waitcnt vmcnt(26)
	ds_write_b32 v35, v99 offset:2376
	s_waitcnt vmcnt(25)
	ds_write_b32 v35, v100 offset:2640
	s_waitcnt vmcnt(24)
	ds_write_b32 v35, v101 offset:2904
	s_waitcnt vmcnt(23)
	ds_write_b32 v35, v102 offset:3168
	s_waitcnt vmcnt(22)
	ds_write_b32 v35, v103 offset:3432
	s_waitcnt vmcnt(21)
	ds_write_b32 v35, v104 offset:3696
	s_waitcnt vmcnt(20)
	ds_write_b32 v35, v105 offset:3960
	s_waitcnt vmcnt(19)
	ds_write_b32 v35, v106 offset:4224
	s_waitcnt vmcnt(18)
	ds_write_b32 v35, v107 offset:4488
	s_waitcnt vmcnt(17)
	ds_write_b32 v35, v108 offset:4752
	s_waitcnt vmcnt(16)
	ds_write_b32 v35, v109 offset:5016
	s_waitcnt vmcnt(15)
	ds_write_b32 v35, v110 offset:5280
	s_waitcnt vmcnt(14)
	ds_write_b32 v35, v111 offset:5544
	s_waitcnt vmcnt(13)
	ds_write_b32 v35, v112 offset:5808
	s_waitcnt vmcnt(12)
	ds_write_b32 v35, v113 offset:6072
	s_waitcnt vmcnt(11)
	ds_write_b32 v35, v114 offset:6336
	s_waitcnt vmcnt(10)
	ds_write_b32 v35, v115 offset:6600
	s_waitcnt vmcnt(9)
	ds_write_b32 v35, v116 offset:6864
	s_waitcnt vmcnt(8)
	ds_write_b32 v35, v117 offset:7128
	s_waitcnt vmcnt(7)
	ds_write_b32 v35, v118 offset:7392
	s_waitcnt vmcnt(6)
	ds_write_b32 v35, v119 offset:7656
	s_waitcnt vmcnt(5)
	ds_write_b32 v35, v120 offset:7920
	s_waitcnt vmcnt(4)
	ds_write_b32 v35, v121 offset:8184
	s_waitcnt lgkmcnt(0)
	ds_read2_b32 v[72:73], v36 offset1:33
	ds_read2_b32 v[74:75], v36 offset0:66 offset1:99
	ds_read2_b32 v[76:77], v36 offset0:132 offset1:165
	ds_read2_b32 v[78:79], v36 offset0:198 offset1:231
	s_waitcnt lgkmcnt(0)
	v_cvt_pk_bf16_f32 v80, v72, v73
	v_cvt_pk_bf16_f32 v81, v74, v75
	v_cvt_pk_bf16_f32 v82, v76, v77
	v_cvt_pk_bf16_f32 v83, v78, v79
	global_store_dwordx4 v84, v[80:83], s[12:13]
	s_add_u32 s12, s12, 0x4000
	s_addc_u32 s13, s13, 0
	ds_read2_b32 v[72:73], v36 offset0:8 offset1:41
	ds_read2_b32 v[74:75], v36 offset0:74 offset1:107
	ds_read2_b32 v[76:77], v36 offset0:140 offset1:173
	ds_read2_b32 v[78:79], v36 offset0:206 offset1:239
	s_waitcnt lgkmcnt(0)
	v_cvt_pk_bf16_f32 v80, v72, v73
	v_cvt_pk_bf16_f32 v81, v74, v75
	v_cvt_pk_bf16_f32 v82, v76, v77
	v_cvt_pk_bf16_f32 v83, v78, v79
	global_store_dwordx4 v84, v[80:83], s[12:13]
	s_add_u32 s12, s12, 0x4000
	s_addc_u32 s13, s13, 0
	ds_read2_b32 v[72:73], v36 offset0:16 offset1:49
	ds_read2_b32 v[74:75], v36 offset0:82 offset1:115
	ds_read2_b32 v[76:77], v36 offset0:148 offset1:181
	ds_read2_b32 v[78:79], v36 offset0:214 offset1:247
	s_waitcnt lgkmcnt(0)
	v_cvt_pk_bf16_f32 v80, v72, v73
	v_cvt_pk_bf16_f32 v81, v74, v75
	v_cvt_pk_bf16_f32 v82, v76, v77
	v_cvt_pk_bf16_f32 v83, v78, v79
	global_store_dwordx4 v84, v[80:83], s[12:13]
	s_add_u32 s12, s12, 0x4000
	s_addc_u32 s13, s13, 0
	ds_read2_b32 v[72:73], v36 offset0:24 offset1:57
	ds_read2_b32 v[74:75], v36 offset0:90 offset1:123
	ds_read2_b32 v[76:77], v36 offset0:156 offset1:189
	ds_read2_b32 v[78:79], v36 offset0:222 offset1:255
	s_waitcnt lgkmcnt(0)
	v_cvt_pk_bf16_f32 v80, v72, v73
	v_cvt_pk_bf16_f32 v81, v74, v75
	v_cvt_pk_bf16_f32 v82, v76, v77
	v_cvt_pk_bf16_f32 v83, v78, v79
	global_store_dwordx4 v84, v[80:83], s[12:13]
	s_branch .Ltr2_pair_done
; #define LAS __attribute__((address_space(3)))
; __device__ __forceinline__ unsigned pk2(float lo, float hi) { f32x2v v = {lo, hi}; b16x2v b = __builtin_convertvector(v, b16x2v); return __builtin_bit_cast(unsigned, b); }
; template <int MODE>
; __device__ __forceinline__ void tr_item(const float* __restrict__ W, int N, bf16_t* WT, int ldk, int row_off, LAS float* scr, int kb, int nb, int lane,
;                                         const float* g, const float* b, float* c1, float* c2) {
;     const int k0 = 64 * kb, n0 = 32 * nb;
;     float tv[32];
; #pragma unroll
;     for (int i = 0; i < 32; ++i) tv[i] = __builtin_nontemporal_load(W + (size_t)(k0 + 2 * i + (lane >> 5)) * N + n0 + (lane & 31));
; #pragma unroll
;     for (int i = 0; i < 32; ++i) scr[(2 * i + (lane >> 5)) * 33 + (lane & 31)] = tv[i];
;     asm volatile("s_waitcnt lgkmcnt(0)" ::: "memory");
;     if (MODE == 2) {
;         const float* vec = (lane < 32) ? g : b; float s = 0.f;
; #pragma unroll 8
;         for (int k = 0; k < 64; ++k) s += vec[k0 + k] * scr[k * 33 + (lane & 31)];
;         atomicAdd(((lane < 32) ? c1 : c2) + n0 + (lane & 31), s);
;     }
;     const int c = lane & 7;
;     float gs[8];
; #pragma unroll
;     for (int i = 0; i < 8; ++i) gs[i] = (MODE == 2) ? g[k0 + 8 * c + i] : 1.0f;
; #pragma unroll
;     for (int j = 0; j < 4; ++j) { const int n = (lane >> 3) + 8 * j; const LAS float* s = scr + (8 * c) * 33 + n;
;         u32x4 o; o.x = pk2(s[0 * 33] * gs[0], s[1 * 33] * gs[1]); o.y = pk2(s[2 * 33] * gs[2], s[3 * 33] * gs[3]); o.z = pk2(s[4 * 33] * gs[4], s[5 * 33] * gs[5]); o.w = pk2(s[6 * 33] * gs[6], s[7 * 33] * gs[7]);
;         const int dr = (MODE == 1) ? win_dest(n0 + n) : (n0 + n);
;         *(u32x4*)(WT + (size_t)(row_off + dr) * ldk + k0 + 8 * c) = o; }
;     asm volatile("s_waitcnt lgkmcnt(0)" ::: "memory");
.Ltr2_b_wout:
	s_sub_u32 s66, s67, 0xa00
	s_lshr_b32 s0, s66, 5
	s_and_b32 s1, s66, 31
	s_mul_i32 s68, s0, 0x40000
	s_lshl_b32 s69, s1, 7
	s_add_u32 s68, s68, s69
	s_add_u32 s68, s64, s68
	s_addc_u32 s69, s65, 0
	global_load_dword v90, v34, s[68:69] nt
	s_add_u32 s68, s68, 0x2000
	s_addc_u32 s69, s69, 0
	global_load_dword v91, v34, s[68:69] nt
	s_add_u32 s68, s68, 0x2000
	s_addc_u32 s69, s69, 0
	global_load_dword v92, v34, s[68:69] nt
	s_add_u32 s68, s68, 0x2000
	s_addc_u32 s69, s69, 0
	global_load_dword v93, v34, s[68:69] nt
	s_add_u32 s68, s68, 0x2000
	s_addc_u32 s69, s69, 0
	global_load_dword v94, v34, s[68:69] nt
	s_add_u32 s68, s68, 0x2000
	s_addc_u32 s69, s69, 0
	global_load_dword v95, v34, s[68:69] nt
	s_add_u32 s68, s68, 0x2000
	s_addc_u32 s69, s69, 0
	global_load_dword v96, v34, s[68:69] nt
	s_add_u32 s68, s68, 0x2000
	s_addc_u32 s69, s69, 0
	global_load_dword v97, v34, s[68:69] nt
	s_add_u32 s68, s68, 0x2000
	s_addc_u32 s69, s69, 0
	global_load_dword v98, v34, s[68:69] nt
	s_add_u32 s68, s68, 0x2000
	s_addc_u32 s69, s69, 0
	global_load_dword v99, v34, s[68:69] nt
	s_add_u32 s68, s68, 0x2000
	s_addc_u32 s69, s69, 0
	global_load_dword v100, v34, s[68:69] nt
	s_add_u32 s68, s68, 0x2000
	s_addc_u32 s69, s69, 0
	global_load_dword v101, v34, s[68:69] nt
	s_add_u32 s68, s68, 0x2000
	s_addc_u32 s69, s69, 0
	global_load_dword v102, v34, s[68:69] nt
	s_add_u32 s68, s68, 0x2000
	s_addc_u32 s69, s69, 0
	global_load_dword v103, v34, s[68:69] nt
	s_add_u32 s68, s68, 0x2000
	s_addc_u32 s69, s69, 0
	global_load_dword v104, v34, s[68:69] nt
	s_add_u32 s68, s68, 0x2000
	s_addc_u32 s69, s69, 0
	global_load_dword v105, v34, s[68:69] nt
	s_add_u32 s68, s68, 0x2000
	s_addc_u32 s69, s69, 0
	global_load_dword v106, v34, s[68:69] nt
	s_add_u32 s68, s68, 0x2000
	s_addc_u32 s69, s69, 0
	global_load_dword v107, v34, s[68:69] nt
	s_add_u32 s68, s68, 0x2000
	s_addc_u32 s69, s69, 0
	global_load_dword v108, v34, s[68:69] nt
	s_add_u32 s68, s68, 0x2000
	s_addc_u32 s69, s69, 0
	global_load_dword v109, v34, s[68:69] nt
	s_add_u32 s68, s68, 0x2000
	s_addc_u32 s69, s69, 0
	global_load_dword v110, v34, s[68:69] nt
	s_add_u32 s68, s68, 0x2000
	s_addc_u32 s69, s69, 0
	global_load_dword v111, v34, s[68:69] nt
	s_add_u32 s68, s68, 0x2000
	s_addc_u32 s69, s69, 0
	global_load_dword v112, v34, s[68:69] nt
	s_add_u32 s68, s68, 0x2000
	s_addc_u32 s69, s69, 0
	global_load_dword v113, v34, s[68:69] nt
	s_add_u32 s68, s68, 0x2000
	s_addc_u32 s69, s69, 0
	global_load_dword v114, v34, s[68:69] nt
	s_add_u32 s68, s68, 0x2000
	s_addc_u32 s69, s69, 0
	global_load_dword v115, v34, s[68:69] nt
	s_add_u32 s68, s68, 0x2000
	s_addc_u32 s69, s69, 0
	global_load_dword v116, v34, s[68:69] nt
	s_add_u32 s68, s68, 0x2000
	s_addc_u32 s69, s69, 0
	global_load_dword v117, v34, s[68:69] nt
	s_add_u32 s68, s68, 0x2000
	s_addc_u32 s69, s69, 0
	global_load_dword v118, v34, s[68:69] nt
	s_add_u32 s68, s68, 0x2000
	s_addc_u32 s69, s69, 0
	global_load_dword v119, v34, s[68:69] nt
	s_add_u32 s68, s68, 0x2000
	s_addc_u32 s69, s69, 0
	global_load_dword v120, v34, s[68:69] nt
	s_add_u32 s68, s68, 0x2000
	s_addc_u32 s69, s69, 0
	s_lshr_b32 s0, s10, 5
	s_and_b32 s1, s10, 31
	s_mul_i32 s12, s1, 0x40000
	s_lshl_b32 s13, s0, 7
	s_add_u32 s12, s12, s13
	s_add_u32 s12, s12, 0x1700000
	s_add_u32 s12, s58, s12
	s_addc_u32 s13, s59, 0
	s_waitcnt vmcnt(62)
	global_load_dword v121, v34, s[68:69] nt
	ds_write_b32 v35, v40
	s_waitcnt vmcnt(62)
	ds_write_b32 v35, v41 offset:264
	s_waitcnt vmcnt(61)
	ds_write_b32 v35, v42 offset:528
	s_waitcnt vmcnt(60)
	ds_write_b32 v35, v43 offset:792
	s_waitcnt vmcnt(59)
	ds_write_b32 v35, v44 offset:1056
	s_waitcnt vmcnt(58)
	ds_write_b32 v35, v45 offset:1320
	s_waitcnt vmcnt(57)
	ds_write_b32 v35, v46 offset:1584
	s_waitcnt vmcnt(56)
	ds_write_b32 v35, v47 offset:1848
	s_waitcnt vmcnt(55)
	ds_write_b32 v35, v48 offset:2112
	s_waitcnt vmcnt(54)
	ds_write_b32 v35, v49 offset:2376
	s_waitcnt vmcnt(53)
	ds_write_b32 v35, v50 offset:2640
	s_waitcnt vmcnt(52)
	ds_write_b32 v35, v51 offset:2904
	s_waitcnt vmcnt(51)
	ds_write_b32 v35, v52 offset:3168
	s_waitcnt vmcnt(50)
	ds_write_b32 v35, v53 offset:3432
	s_waitcnt vmcnt(49)
	ds_write_b32 v35, v54 offset:3696
	s_waitcnt vmcnt(48)
	ds_write_b32 v35, v55 offset:3960
	s_waitcnt vmcnt(47)
	ds_write_b32 v35, v56 offset:4224
	s_waitcnt vmcnt(46)
	ds_write_b32 v35, v57 offset:4488
	s_waitcnt vmcnt(45)
	ds_write_b32 v35, v58 offset:4752
	s_waitcnt vmcnt(44)
	ds_write_b32 v35, v59 offset:5016
	s_waitcnt vmcnt(43)
	ds_write_b32 v35, v60 offset:5280
	s_waitcnt vmcnt(42)
	ds_write_b32 v35, v61 offset:5544
	s_waitcnt vmcnt(41)
	ds_write_b32 v35, v62 offset:5808
	s_waitcnt vmcnt(40)
	ds_write_b32 v35, v63 offset:6072
	s_waitcnt vmcnt(39)
	ds_write_b32 v35, v64 offset:6336
	s_waitcnt vmcnt(38)
	ds_write_b32 v35, v65 offset:6600
	s_waitcnt vmcnt(37)
	ds_write_b32 v35, v66 offset:6864
	s_waitcnt vmcnt(36)
	ds_write_b32 v35, v67 offset:7128
	s_waitcnt vmcnt(35)
	ds_write_b32 v35, v68 offset:7392
	s_waitcnt vmcnt(34)
	ds_write_b32 v35, v69 offset:7656
	s_waitcnt vmcnt(33)
	ds_write_b32 v35, v70 offset:7920
	s_waitcnt vmcnt(32)
	ds_write_b32 v35, v71 offset:8184
	s_waitcnt lgkmcnt(0)
	ds_read2_b32 v[72:73], v36 offset1:33
	ds_read2_b32 v[74:75], v36 offset0:66 offset1:99
	ds_read2_b32 v[76:77], v36 offset0:132 offset1:165
	ds_read2_b32 v[78:79], v36 offset0:198 offset1:231
	s_waitcnt lgkmcnt(0)
	v_cvt_pk_bf16_f32 v80, v72, v73
	v_cvt_pk_bf16_f32 v81, v74, v75
	v_cvt_pk_bf16_f32 v82, v76, v77
	v_cvt_pk_bf16_f32 v83, v78, v79
	global_store_dwordx4 v37, v[80:83], s[12:13]
	s_add_u32 s12, s12, 0x10000
	s_addc_u32 s13, s13, 0
	ds_read2_b32 v[72:73], v36 offset0:8 offset1:41
	ds_read2_b32 v[74:75], v36 offset0:74 offset1:107
	ds_read2_b32 v[76:77], v36 offset0:140 offset1:173
	ds_read2_b32 v[78:79], v36 offset0:206 offset1:239
	s_waitcnt lgkmcnt(0)
; #define LAS __attribute__((address_space(3)))
; __device__ __forceinline__ unsigned pk2(float lo, float hi) { f32x2v v = {lo, hi}; b16x2v b = __builtin_convertvector(v, b16x2v); return __builtin_bit_cast(unsigned, b); }
; template <int MODE>
; __device__ __forceinline__ void tr_item(const float* __restrict__ W, int N, bf16_t* WT, int ldk, int row_off, LAS float* scr, int kb, int nb, int lane,
;                                         const float* g, const float* b, float* c1, float* c2) {
;     const int k0 = 64 * kb, n0 = 32 * nb;
;     float tv[32];
; #pragma unroll
;     for (int i = 0; i < 32; ++i) tv[i] = __builtin_nontemporal_load(W + (size_t)(k0 + 2 * i + (lane >> 5)) * N + n0 + (lane & 31));
; #pragma unroll
;     for (int i = 0; i < 32; ++i) scr[(2 * i + (lane >> 5)) * 33 + (lane & 31)] = tv[i];
;     asm volatile("s_waitcnt lgkmcnt(0)" ::: "memory");
;     if (MODE == 2) {
;         const float* vec = (lane < 32) ? g : b; float s = 0.f;
; #pragma unroll 8
;         for (int k = 0; k < 64; ++k) s += vec[k0 + k] * scr[k * 33 + (lane & 31)];
;         atomicAdd(((lane < 32) ? c1 : c2) + n0 + (lane & 31), s);
;     }
;     const int c = lane & 7;
;     float gs[8];
; #pragma unroll
;     for (int i = 0; i < 8; ++i) gs[i] = (MODE == 2) ? g[k0 + 8 * c + i] : 1.0f;
; #pragma unroll
;     for (int j = 0; j < 4; ++j) { const int n = (lane >> 3) + 8 * j; const LAS float* s = scr + (8 * c) * 33 + n;
;         u32x4 o; o.x = pk2(s[0 * 33] * gs[0], s[1 * 33] * gs[1]); o.y = pk2(s[2 * 33] * gs[2], s[3 * 33] * gs[3]); o.z = pk2(s[4 * 33] * gs[4], s[5 * 33] * gs[5]); o.w = pk2(s[6 * 33] * gs[6], s[7 * 33] * gs[7]);
;         const int dr = (MODE == 1) ? win_dest(n0 + n) : (n0 + n);
;         *(u32x4*)(WT + (size_t)(row_off + dr) * ldk + k0 + 8 * c) = o; }
;     asm volatile("s_waitcnt lgkmcnt(0)" ::: "memory");
	v_cvt_pk_bf16_f32 v80, v72, v73
	v_cvt_pk_bf16_f32 v81, v74, v75
	v_cvt_pk_bf16_f32 v82, v76, v77
	v_cvt_pk_bf16_f32 v83, v78, v79
	global_store_dwordx4 v37, v[80:83], s[12:13]
	s_add_u32 s12, s12, 0x10000
	s_addc_u32 s13, s13, 0
	ds_read2_b32 v[72:73], v36 offset0:16 offset1:49
	ds_read2_b32 v[74:75], v36 offset0:82 offset1:115
	ds_read2_b32 v[76:77], v36 offset0:148 offset1:181
	ds_read2_b32 v[78:79], v36 offset0:214 offset1:247
	s_waitcnt lgkmcnt(0)
	v_cvt_pk_bf16_f32 v80, v72, v73
	v_cvt_pk_bf16_f32 v81, v74, v75
	v_cvt_pk_bf16_f32 v82, v76, v77
	v_cvt_pk_bf16_f32 v83, v78, v79
	global_store_dwordx4 v37, v[80:83], s[12:13]
	s_add_u32 s12, s12, 0x10000
	s_addc_u32 s13, s13, 0
	ds_read2_b32 v[72:73], v36 offset0:24 offset1:57
	ds_read2_b32 v[74:75], v36 offset0:90 offset1:123
	ds_read2_b32 v[76:77], v36 offset0:156 offset1:189
	ds_read2_b32 v[78:79], v36 offset0:222 offset1:255
	s_waitcnt lgkmcnt(0)
	v_cvt_pk_bf16_f32 v80, v72, v73
	v_cvt_pk_bf16_f32 v81, v74, v75
	v_cvt_pk_bf16_f32 v82, v76, v77
	v_cvt_pk_bf16_f32 v83, v78, v79
	global_store_dwordx4 v37, v[80:83], s[12:13]
	s_lshr_b32 s0, s66, 5
	s_and_b32 s1, s66, 31
	s_mul_i32 s12, s1, 0x10000
	s_lshl_b32 s13, s0, 7
	s_add_u32 s12, s12, s13
	s_add_u32 s12, s12, 0x900000
	s_add_u32 s12, s58, s12
	s_addc_u32 s13, s59, 0
	s_waitcnt vmcnt(35)
	ds_write_b32 v35, v90
	s_waitcnt vmcnt(34)
	ds_write_b32 v35, v91 offset:264
	s_waitcnt vmcnt(33)
	ds_write_b32 v35, v92 offset:528
	s_waitcnt vmcnt(32)
	ds_write_b32 v35, v93 offset:792
	s_waitcnt vmcnt(31)
	ds_write_b32 v35, v94 offset:1056
	s_waitcnt vmcnt(30)
	ds_write_b32 v35, v95 offset:1320
	s_waitcnt vmcnt(29)
	ds_write_b32 v35, v96 offset:1584
	s_waitcnt vmcnt(28)
	ds_write_b32 v35, v97 offset:1848
	s_waitcnt vmcnt(27)
	ds_write_b32 v35, v98 offset:2112
	s_waitcnt vmcnt(26)
	ds_write_b32 v35, v99 offset:2376
	s_waitcnt vmcnt(25)
	ds_write_b32 v35, v100 offset:2640
	s_waitcnt vmcnt(24)
	ds_write_b32 v35, v101 offset:2904
	s_waitcnt vmcnt(23)
	ds_write_b32 v35, v102 offset:3168
	s_waitcnt vmcnt(22)
	ds_write_b32 v35, v103 offset:3432
	s_waitcnt vmcnt(21)
	ds_write_b32 v35, v104 offset:3696
	s_waitcnt vmcnt(20)
	ds_write_b32 v35, v105 offset:3960
	s_waitcnt vmcnt(19)
	ds_write_b32 v35, v106 offset:4224
	s_waitcnt vmcnt(18)
	ds_write_b32 v35, v107 offset:4488
	s_waitcnt vmcnt(17)
	ds_write_b32 v35, v108 offset:4752
	s_waitcnt vmcnt(16)
	ds_write_b32 v35, v109 offset:5016
	s_waitcnt vmcnt(15)
	ds_write_b32 v35, v110 offset:5280
	s_waitcnt vmcnt(14)
	ds_write_b32 v35, v111 offset:5544
	s_waitcnt vmcnt(13)
	ds_write_b32 v35, v112 offset:5808
	s_waitcnt vmcnt(12)
	ds_write_b32 v35, v113 offset:6072
	s_waitcnt vmcnt(11)
	ds_write_b32 v35, v114 offset:6336
	s_waitcnt vmcnt(10)
	ds_write_b32 v35, v115 offset:6600
	s_waitcnt vmcnt(9)
	ds_write_b32 v35, v116 offset:6864
	s_waitcnt vmcnt(8)
	ds_write_b32 v35, v117 offset:7128
	s_waitcnt vmcnt(7)
	ds_write_b32 v35, v118 offset:7392
	s_waitcnt vmcnt(6)
	ds_write_b32 v35, v119 offset:7656
	s_waitcnt vmcnt(5)
	ds_write_b32 v35, v120 offset:7920
	s_waitcnt vmcnt(4)
	ds_write_b32 v35, v121 offset:8184
	s_waitcnt lgkmcnt(0)
	ds_read2_b32 v[72:73], v36 offset1:33
	ds_read2_b32 v[74:75], v36 offset0:66 offset1:99
	ds_read2_b32 v[76:77], v36 offset0:132 offset1:165
	ds_read2_b32 v[78:79], v36 offset0:198 offset1:231
	s_waitcnt lgkmcnt(0)
	v_cvt_pk_bf16_f32 v80, v72, v73
	v_cvt_pk_bf16_f32 v81, v74, v75
	v_cvt_pk_bf16_f32 v82, v76, v77
	v_cvt_pk_bf16_f32 v83, v78, v79
	global_store_dwordx4 v84, v[80:83], s[12:13]
	s_add_u32 s12, s12, 0x4000
	s_addc_u32 s13, s13, 0
	ds_read2_b32 v[72:73], v36 offset0:8 offset1:41
	ds_read2_b32 v[74:75], v36 offset0:74 offset1:107
	ds_read2_b32 v[76:77], v36 offset0:140 offset1:173
	ds_read2_b32 v[78:79], v36 offset0:206 offset1:239
	s_waitcnt lgkmcnt(0)
	v_cvt_pk_bf16_f32 v80, v72, v73
	v_cvt_pk_bf16_f32 v81, v74, v75
	v_cvt_pk_bf16_f32 v82, v76, v77
	v_cvt_pk_bf16_f32 v83, v78, v79
	global_store_dwordx4 v84, v[80:83], s[12:13]
	s_add_u32 s12, s12, 0x4000
	s_addc_u32 s13, s13, 0
	ds_read2_b32 v[72:73], v36 offset0:16 offset1:49
	ds_read2_b32 v[74:75], v36 offset0:82 offset1:115
	ds_read2_b32 v[76:77], v36 offset0:148 offset1:181
	ds_read2_b32 v[78:79], v36 offset0:214 offset1:247
	s_waitcnt lgkmcnt(0)
	v_cvt_pk_bf16_f32 v80, v72, v73
	v_cvt_pk_bf16_f32 v81, v74, v75
	v_cvt_pk_bf16_f32 v82, v76, v77
	v_cvt_pk_bf16_f32 v83, v78, v79
	global_store_dwordx4 v84, v[80:83], s[12:13]
	s_add_u32 s12, s12, 0x4000
	s_addc_u32 s13, s13, 0
	ds_read2_b32 v[72:73], v36 offset0:24 offset1:57
	ds_read2_b32 v[74:75], v36 offset0:90 offset1:123
	ds_read2_b32 v[76:77], v36 offset0:156 offset1:189
	ds_read2_b32 v[78:79], v36 offset0:222 offset1:255
	s_waitcnt lgkmcnt(0)
	v_cvt_pk_bf16_f32 v80, v72, v73
	v_cvt_pk_bf16_f32 v81, v74, v75
	v_cvt_pk_bf16_f32 v82, v76, v77
	v_cvt_pk_bf16_f32 v83, v78, v79
	global_store_dwordx4 v84, v[80:83], s[12:13]
	s_branch .Ltr2_pair_done
; #define LAS __attribute__((address_space(3)))
; template <int MODE>
; __device__ __forceinline__ void tr_item(const float* __restrict__ W, int N, bf16_t* WT, int ldk, int row_off, LAS float* scr, int kb, int nb, int lane,
;                                         const float* g, const float* b, float* c1, float* c2) {
;     const int k0 = 64 * kb, n0 = 32 * nb;
;     float tv[32];
; #pragma unroll
;     for (int i = 0; i < 32; ++i) tv[i] = __builtin_nontemporal_load(W + (size_t)(k0 + 2 * i + (lane >> 5)) * N + n0 + (lane & 31));
; #pragma unroll
;     for (int i = 0; i < 32; ++i) scr[(2 * i + (lane >> 5)) * 33 + (lane & 31)] = tv[i];
;     asm volatile("s_waitcnt lgkmcnt(0)" ::: "memory");
;     if (MODE == 2) {
;         const float* vec = (lane < 32) ? g : b; float s = 0.f;
; #pragma unroll 8
;         for (int k = 0; k < 64; ++k) s += vec[k0 + k] * scr[k * 33 + (lane & 31)];
;         atomicAdd(((lane < 32) ? c1 : c2) + n0 + (lane & 31), s);
;     }
;     const int c = lane & 7;
;     float gs[8];
; #pragma unroll
;     for (int i = 0; i < 8; ++i) gs[i] = (MODE == 2) ? g[k0 + 8 * c + i] : 1.0f;
; #pragma unroll
;     for (int j = 0; j < 4; ++j) { const int n = (lane >> 3) + 8 * j; const LAS float* s = scr + (8 * c) * 33 + n;
;         u32x4 o; o.x = pk2(s[0 * 33] * gs[0], s[1 * 33] * gs[1]); o.y = pk2(s[2 * 33] * gs[2], s[3 * 33] * gs[3]); o.z = pk2(s[4 * 33] * gs[4], s[5 * 33] * gs[5]); o.w = pk2(s[6 * 33] * gs[6], s[7 * 33] * gs[7]);
;         const int dr = (MODE == 1) ? win_dest(n0 + n) : (n0 + n);
;         *(u32x4*)(WT + (size_t)(row_off + dr) * ldk + k0 + 8 * c) = o; }
;     asm volatile("s_waitcnt lgkmcnt(0)" ::: "memory");
; __device__ __forceinline__ void p0_prologue(const Args& p, LAS unsigned char* lds, int G, int bid, int tid) {
;     ...
;     for (int it = gw; it < NITEMS; it += NGW) {
;         int r = it;
;         if (r < I_IN) { tr_item<1>(p.w_in(), DIN, p.Win_t(), DM, 0, scr, r / 48, r % 48, lane, nullptr, nullptr, nullptr, nullptr); continue; } r -= I_IN;
;         if (r < I_K) { tr_item<0>(p.xk_w(), DM, p.Wkv_t(), DM, 0, scr, r / 32, r % 32, lane, nullptr, nullptr, nullptr, nullptr); continue; } r -= I_K;
;         if (r < I_V) { tr_item<0>(p.xv_w(), DM, p.Wkv_t(), DM, DM, scr, r / 32, r % 32, lane, nullptr, nullptr, nullptr, nullptr); continue; } r -= I_V;
.Ltr2_only_a:
	s_lshr_b32 s0, s10, 5
	s_and_b32 s1, s10, 31
	s_mul_i32 s12, s1, 0x40000
	s_lshl_b32 s13, s0, 7
	s_add_u32 s12, s12, s13
	s_add_u32 s12, s12, 0x1700000
	s_add_u32 s12, s58, s12
	s_addc_u32 s13, s59, 0
	s_waitcnt vmcnt(31)
	ds_write_b32 v35, v40
	s_waitcnt vmcnt(30)
	ds_write_b32 v35, v41 offset:264
	s_waitcnt vmcnt(29)
	ds_write_b32 v35, v42 offset:528
	s_waitcnt vmcnt(28)
	ds_write_b32 v35, v43 offset:792
	s_waitcnt vmcnt(27)
	ds_write_b32 v35, v44 offset:1056
	s_waitcnt vmcnt(26)
	ds_write_b32 v35, v45 offset:1320
	s_waitcnt vmcnt(25)
	ds_write_b32 v35, v46 offset:1584
	s_waitcnt vmcnt(24)
	ds_write_b32 v35, v47 offset:1848
	s_waitcnt vmcnt(23)
	ds_write_b32 v35, v48 offset:2112
	s_waitcnt vmcnt(22)
	ds_write_b32 v35, v49 offset:2376
	s_waitcnt vmcnt(21)
	ds_write_b32 v35, v50 offset:2640
	s_waitcnt vmcnt(20)
	ds_write_b32 v35, v51 offset:2904
	s_waitcnt vmcnt(19)
	ds_write_b32 v35, v52 offset:3168
	s_waitcnt vmcnt(18)
	ds_write_b32 v35, v53 offset:3432
	s_waitcnt vmcnt(17)
	ds_write_b32 v35, v54 offset:3696
	s_waitcnt vmcnt(16)
	ds_write_b32 v35, v55 offset:3960
	s_waitcnt vmcnt(15)
	ds_write_b32 v35, v56 offset:4224
	s_waitcnt vmcnt(14)
	ds_write_b32 v35, v57 offset:4488
	s_waitcnt vmcnt(13)
	ds_write_b32 v35, v58 offset:4752
	s_waitcnt vmcnt(12)
	ds_write_b32 v35, v59 offset:5016
	s_waitcnt vmcnt(11)
	ds_write_b32 v35, v60 offset:5280
	s_waitcnt vmcnt(10)
	ds_write_b32 v35, v61 offset:5544
	s_waitcnt vmcnt(9)
	ds_write_b32 v35, v62 offset:5808
	s_waitcnt vmcnt(8)
	ds_write_b32 v35, v63 offset:6072
	s_waitcnt vmcnt(7)
	ds_write_b32 v35, v64 offset:6336
	s_waitcnt vmcnt(6)
	ds_write_b32 v35, v65 offset:6600
	s_waitcnt vmcnt(5)
	ds_write_b32 v35, v66 offset:6864
	s_waitcnt vmcnt(4)
	ds_write_b32 v35, v67 offset:7128
	s_waitcnt vmcnt(3)
	ds_write_b32 v35, v68 offset:7392
	s_waitcnt vmcnt(2)
	ds_write_b32 v35, v69 offset:7656
	s_waitcnt vmcnt(1)
	ds_write_b32 v35, v70 offset:7920
	s_waitcnt vmcnt(0)
	ds_write_b32 v35, v71 offset:8184
	s_waitcnt lgkmcnt(0)
	ds_read2_b32 v[72:73], v36 offset1:33
	ds_read2_b32 v[74:75], v36 offset0:66 offset1:99
	ds_read2_b32 v[76:77], v36 offset0:132 offset1:165
	ds_read2_b32 v[78:79], v36 offset0:198 offset1:231
	s_waitcnt lgkmcnt(0)
	v_cvt_pk_bf16_f32 v80, v72, v73
	v_cvt_pk_bf16_f32 v81, v74, v75
	v_cvt_pk_bf16_f32 v82, v76, v77
	v_cvt_pk_bf16_f32 v83, v78, v79
	global_store_dwordx4 v37, v[80:83], s[12:13]
	s_add_u32 s12, s12, 0x10000
	s_addc_u32 s13, s13, 0
	ds_read2_b32 v[72:73], v36 offset0:8 offset1:41
	ds_read2_b32 v[74:75], v36 offset0:74 offset1:107
	ds_read2_b32 v[76:77], v36 offset0:140 offset1:173
	ds_read2_b32 v[78:79], v36 offset0:206 offset1:239
	s_waitcnt lgkmcnt(0)
	v_cvt_pk_bf16_f32 v80, v72, v73
	v_cvt_pk_bf16_f32 v81, v74, v75
	v_cvt_pk_bf16_f32 v82, v76, v77
	v_cvt_pk_bf16_f32 v83, v78, v79
	global_store_dwordx4 v37, v[80:83], s[12:13]
	s_add_u32 s12, s12, 0x10000
	s_addc_u32 s13, s13, 0
	ds_read2_b32 v[72:73], v36 offset0:16 offset1:49
	ds_read2_b32 v[74:75], v36 offset0:82 offset1:115
	ds_read2_b32 v[76:77], v36 offset0:148 offset1:181
	ds_read2_b32 v[78:79], v36 offset0:214 offset1:247
	s_waitcnt lgkmcnt(0)
	v_cvt_pk_bf16_f32 v80, v72, v73
	v_cvt_pk_bf16_f32 v81, v74, v75
	v_cvt_pk_bf16_f32 v82, v76, v77
	v_cvt_pk_bf16_f32 v83, v78, v79
	global_store_dwordx4 v37, v[80:83], s[12:13]
	s_add_u32 s12, s12, 0x10000
	s_addc_u32 s13, s13, 0
	ds_read2_b32 v[72:73], v36 offset0:24 offset1:57
	ds_read2_b32 v[74:75], v36 offset0:90 offset1:123
	ds_read2_b32 v[76:77], v36 offset0:156 offset1:189
	ds_read2_b32 v[78:79], v36 offset0:222 offset1:255
	s_waitcnt lgkmcnt(0)
	v_cvt_pk_bf16_f32 v80, v72, v73
	v_cvt_pk_bf16_f32 v81, v74, v75
	v_cvt_pk_bf16_f32 v82, v76, v77
	v_cvt_pk_bf16_f32 v83, v78, v79
	global_store_dwordx4 v37, v[80:83], s[12:13]
.Ltr2_pair_done:
	s_add_u32 s10, s67, s11
